# strategy 4 (static priority raise): one s_setprio 1 for the younger wave half (wr==1, waves 4-7) at entry of the FFN gate/up K-loop, reset to 0 at loop exit; no per-phase flips
# speedup vs baseline: 1.0070x; 1.0048x over previous
; #define PG8_STAGE(bufoff, gbase, voff) do { _Pragma("unroll") for (int _i = 0; _i < 2; ++_i) \
;         __builtin_amdgcn_global_load_lds((const unsigned*)((const char*)(gbase) + (voff)[_i]), (LAS unsigned*)(lds + (bufoff) + ldsw + _i * 8192), 16, 0, 0); } while (0)
; #define PG8_LDA(dst, b, h) do { _Pragma("unroll") for (int m = 0; m < 4; ++m) _Pragma("unroll") for (int k = 0; k < 2; ++k) dst[m][k] = *(const LAS bf16x8*)(lds + PG8_SA(b, h) + aoff + m * 2048 + k * 1024); } while (0)
; #define PG8_LDB(dst, b, h) do { _Pragma("unroll") for (int n = 0; n < 2; ++n) _Pragma("unroll") for (int k = 0; k < 2; ++k) dst[n][k] = *(const LAS bf16x8*)(lds + PG8_SB(b, h) + boff + n * 2048 + k * 1024); } while (0)
; #define PG8_MMA(ai, bj, At, Bt) do { __builtin_amdgcn_s_setprio(1); _Pragma("unroll") for (int m = 0; m < 4; ++m) _Pragma("unroll") for (int n = 0; n < 2; ++n) _Pragma("unroll") for (int k = 0; k < 2; ++k) \
;         acc[ai][bj][m][n] = __builtin_amdgcn_mfma_f32_16x16x32_bf16(Bt[n][k], At[m][k], acc[ai][bj][m][n], 0, 0, 0); __builtin_amdgcn_s_setprio(0); } while (0)
; #define PG8_BAR __builtin_amdgcn_s_barrier()
; template <class Epi, class Sched>
; __device__ __forceinline__ void gemm_phase(LAS unsigned char* lds, const Gemm g, const Sched& S, const Epi& E) {
;     ...
;         const bool has_next = S.next(ui + 1, nxt);
;         const char* nA = has_next ? (const char*)g.A + (size_t)nxt.pm * tstepA + (size_t)nxt.pn * apn : cA; const char* nB = has_next ? (const char*)g.Bt + (size_t)nxt.pn * tstepB : cB;
;         for (int t = 0; t < nt; t += 2) {
;             const bool last = (t == nt - 2);
;             const char* a1 = cA + (size_t)(t + 1) * kstep;
;             const char* a2 = last ? nA : cA + (size_t)(t + 2) * kstep; const char* b2 = last ? nB : cB + (size_t)(t + 2) * kstep;
;             const char* a3 = a2 + kstep; const char* b3 = b2 + kstep;
;             PG8_LDB(B0, 0, 0); PG8_LDB(B1, 0, 1); PG8_SCHED; PG8_LDA(At, 0, 0); PG8_STAGE(PG8_SA(1, 1), a1 + hstepA, voffA);
;             PG8_WAIT_V(8); PG8_WAIT_L(0); PG8_BAR; PG8_MMA(0, 0, At, B0); PG8_MMA(0, 1, At, B1); PG8_BAR; PG8_SCHED;
;             PG8_LDA(At, 0, 1); PG8_STAGE(PG8_SB(0, 0), b2, voffB); PG8_STAGE(PG8_SB(0, 1), b2 + hstepB, voffB); PG8_STAGE(PG8_SA(0, 0), a2, voffA);
;             PG8_WAIT_V(8); PG8_WAIT_L(0); PG8_BAR; PG8_MMA(1, 0, At, B0); PG8_MMA(1, 1, At, B1); PG8_BAR; PG8_SCHED;
.LBB0_717:
	s_ashr_i32 s23, s22, 31
	s_lshl_b64 s[14:15], s[22:23], 19
	s_add_u32 s34, s84, s14
	s_addc_u32 s35, s85, s15
	s_and_b64 s[14:15], s[42:43], exec
	s_cselect_b32 s23, s35, s7
	s_cselect_b32 s53, s34, s6
	s_ashr_i32 s19, s18, 31
	s_lshl_b64 s[14:15], s[18:19], 19
	s_add_u32 s40, s28, s14
	s_addc_u32 s41, s48, s15
	s_and_b64 s[14:15], s[42:43], exec
	s_cselect_b32 s19, s41, s47
	s_cselect_b32 s54, s40, s46
	s_add_u32 s44, s6, 0x40080
	s_addc_u32 s45, s7, 0
	s_add_u32 s46, s46, 0x100
	s_addc_u32 s47, s47, 0
	s_mov_b32 s55, -2
	s_cmp_eq_u64 s[16:17], 0
	s_cbranch_scc0 .Lprio_gu
	s_setprio 1
.Lprio_gu:
	s_add_u32 s0, s44, 0xfffc0080
	s_addc_u32 s6, s45, -1
	s_add_i32 s26, 0, 0x10000
	s_cmp_eq_u32 s55, 12
	s_cselect_b32 s15, s23, s6
	s_cselect_b32 s14, s53, s0
	v_add_u32_e32 v153, s26, v148
	s_cselect_b32 s7, s19, s47
	s_cselect_b32 s6, s54, s46
	s_add_i32 s0, 0, 0x14000
	ds_read_b128 v[142:145], v153
	ds_read_b128 v[154:157], v153 offset:1024
	ds_read_b128 v[162:165], v153 offset:2048
	ds_read_b128 v[166:169], v153 offset:3072
	v_add_u32_e32 v153, s0, v148
	ds_read_b128 v[170:173], v153
	ds_read_b128 v[174:177], v153 offset:1024
	ds_read_b128 v[190:193], v153 offset:2048
	ds_read_b128 v[196:199], v153 offset:3072
	v_lshl_add_u64 v[158:159], s[44:45], 0, v[138:139]
	s_add_i32 m0, s49, 0xc000
	ds_read_b128 v[200:203], v152
	ds_read_b128 v[204:207], v152 offset:1024
	ds_read_b128 v[208:211], v152 offset:2048
	ds_read_b128 v[212:215], v152 offset:3072
	ds_read_b128 v[216:219], v152 offset:4096
	ds_read_b128 v[220:223], v152 offset:5120
	ds_read_b128 v[224:227], v152 offset:6144
	ds_read_b128 v[228:231], v152 offset:7168
	global_load_lds_dwordx4 v[158:159], off
	v_lshl_add_u64 v[158:159], s[44:45], 0, v[140:141]
	s_add_i32 m0, s49, 0xe000
	s_nop 0
	global_load_lds_dwordx4 v[158:159], off
	s_waitcnt vmcnt(8)
	s_waitcnt lgkmcnt(0)
	s_barrier
	s_waitcnt lgkmcnt(0)
	v_mfma_f32_16x16x32_bf16 v[128:131], v[142:145], v[200:203], 0
	v_mfma_f32_16x16x32_bf16 v[124:127], v[162:165], v[200:203], 0
	v_mfma_f32_16x16x32_bf16 v[112:115], v[142:145], v[208:211], 0
	v_mfma_f32_16x16x32_bf16 v[108:111], v[162:165], v[208:211], 0
	v_mfma_f32_16x16x32_bf16 v[96:99], v[142:145], v[216:219], 0
	v_mfma_f32_16x16x32_bf16 v[92:95], v[162:165], v[216:219], 0
	v_mfma_f32_16x16x32_bf16 v[80:83], v[142:145], v[224:227], 0
	v_mfma_f32_16x16x32_bf16 v[76:79], v[162:165], v[224:227], 0
	v_mfma_f32_16x16x32_bf16 v[128:131], v[154:157], v[204:207], v[128:131]
	v_mfma_f32_16x16x32_bf16 v[124:127], v[166:169], v[204:207], v[124:127]
	v_mfma_f32_16x16x32_bf16 v[112:115], v[154:157], v[212:215], v[112:115]
	v_mfma_f32_16x16x32_bf16 v[108:111], v[166:169], v[212:215], v[108:111]
	v_mfma_f32_16x16x32_bf16 v[96:99], v[154:157], v[220:223], v[96:99]
	v_mfma_f32_16x16x32_bf16 v[92:95], v[166:169], v[220:223], v[92:95]
	v_mfma_f32_16x16x32_bf16 v[80:83], v[154:157], v[228:231], v[80:83]
	v_mfma_f32_16x16x32_bf16 v[76:79], v[166:169], v[228:231], v[76:79]
	v_mfma_f32_16x16x32_bf16 v[120:123], v[170:173], v[200:203], 0
	v_mfma_f32_16x16x32_bf16 v[116:119], v[190:193], v[200:203], 0
	v_mfma_f32_16x16x32_bf16 v[104:107], v[170:173], v[208:211], 0
	v_mfma_f32_16x16x32_bf16 v[100:103], v[190:193], v[208:211], 0
	v_mfma_f32_16x16x32_bf16 v[88:91], v[170:173], v[216:219], 0
	v_mfma_f32_16x16x32_bf16 v[84:87], v[190:193], v[216:219], 0
	v_mfma_f32_16x16x32_bf16 v[72:75], v[170:173], v[224:227], 0
	v_mfma_f32_16x16x32_bf16 v[68:71], v[190:193], v[224:227], 0
	v_mfma_f32_16x16x32_bf16 v[120:123], v[174:177], v[204:207], v[120:123]
	v_mfma_f32_16x16x32_bf16 v[116:119], v[196:199], v[204:207], v[116:119]
	v_mfma_f32_16x16x32_bf16 v[104:107], v[174:177], v[212:215], v[104:107]
	v_mfma_f32_16x16x32_bf16 v[100:103], v[196:199], v[212:215], v[100:103]
	v_mfma_f32_16x16x32_bf16 v[88:91], v[174:177], v[220:223], v[88:91]
	v_mfma_f32_16x16x32_bf16 v[84:87], v[196:199], v[220:223], v[84:87]
	v_mfma_f32_16x16x32_bf16 v[72:75], v[174:177], v[228:231], v[72:75]
	v_mfma_f32_16x16x32_bf16 v[68:71], v[196:199], v[228:231], v[68:71]
	s_barrier
	s_add_i32 s26, s26, s20
	v_lshl_add_u64 v[158:159], s[6:7], 0, v[160:161]
	s_mov_b32 m0, s26
	ds_read_b128 v[200:203], v152 offset:16384
	ds_read_b128 v[204:207], v152 offset:17408
	ds_read_b128 v[208:211], v152 offset:18432
	ds_read_b128 v[212:215], v152 offset:19456
	ds_read_b128 v[216:219], v152 offset:20480
	ds_read_b128 v[220:223], v152 offset:21504
	ds_read_b128 v[224:227], v152 offset:22528
	ds_read_b128 v[228:231], v152 offset:23552
	global_load_lds_dwordx4 v[158:159], off
	s_add_i32 m0, s26, 0x2000
	s_add_u32 s56, s6, 0x40000
	v_lshl_add_u64 v[232:233], s[6:7], 0, v[136:137]
	s_addc_u32 s57, s7, 0
	s_add_i32 s0, s0, s20
	global_load_lds_dwordx4 v[232:233], off
	v_lshl_add_u64 v[234:235], s[56:57], 0, v[160:161]
	s_mov_b32 m0, s0
	v_lshl_add_u64 v[236:237], s[14:15], 0, v[134:135]
	global_load_lds_dwordx4 v[234:235], off
	v_lshl_add_u64 v[234:235], s[56:57], 0, v[136:137]
	s_add_i32 m0, s0, 0x2000
	s_nop 0
	global_load_lds_dwordx4 v[234:235], off
	v_lshl_add_u64 v[234:235], s[14:15], 0, v[132:133]
	s_mov_b32 m0, s49
	s_nop 0
	global_load_lds_dwordx4 v[234:235], off
	s_mov_b32 m0, s50
	s_nop 0
	global_load_lds_dwordx4 v[236:237], off
	s_waitcnt vmcnt(8)
	s_waitcnt lgkmcnt(0)
	s_barrier
; #define PG8_STAGE(bufoff, gbase, voff) do { _Pragma("unroll") for (int _i = 0; _i < 2; ++_i) \
;         __builtin_amdgcn_global_load_lds((const unsigned*)((const char*)(gbase) + (voff)[_i]), (LAS unsigned*)(lds + (bufoff) + ldsw + _i * 8192), 16, 0, 0); } while (0)
; #define PG8_LDA(dst, b, h) do { _Pragma("unroll") for (int m = 0; m < 4; ++m) _Pragma("unroll") for (int k = 0; k < 2; ++k) dst[m][k] = *(const LAS bf16x8*)(lds + PG8_SA(b, h) + aoff + m * 2048 + k * 1024); } while (0)
; #define PG8_LDB(dst, b, h) do { _Pragma("unroll") for (int n = 0; n < 2; ++n) _Pragma("unroll") for (int k = 0; k < 2; ++k) dst[n][k] = *(const LAS bf16x8*)(lds + PG8_SB(b, h) + boff + n * 2048 + k * 1024); } while (0)
; #define PG8_MMA(ai, bj, At, Bt) do { __builtin_amdgcn_s_setprio(1); _Pragma("unroll") for (int m = 0; m < 4; ++m) _Pragma("unroll") for (int n = 0; n < 2; ++n) _Pragma("unroll") for (int k = 0; k < 2; ++k) \
;         acc[ai][bj][m][n] = __builtin_amdgcn_mfma_f32_16x16x32_bf16(Bt[n][k], At[m][k], acc[ai][bj][m][n], 0, 0, 0); __builtin_amdgcn_s_setprio(0); } while (0)
; #define PG8_WAIT_V(n) asm volatile("s_waitcnt vmcnt(" #n ")" ::: "memory")
; #define PG8_WAIT_L(n) asm volatile("s_waitcnt lgkmcnt(" #n ")" ::: "memory")
; #define PG8_BAR __builtin_amdgcn_s_barrier()
; #define PG8_SCHED __builtin_amdgcn_sched_barrier(0)
; template <class Epi, class Sched>
; __device__ __forceinline__ void gemm_phase(LAS unsigned char* lds, const Gemm g, const Sched& S, const Epi& E) {
;     ...
;             PG8_WAIT_V(8); PG8_WAIT_L(0); PG8_BAR; PG8_MMA(1, 0, At, B0); PG8_MMA(1, 1, At, B1); PG8_BAR; PG8_SCHED;
;             PG8_LDB(B0, 1, 0); PG8_LDB(B1, 1, 1); PG8_SCHED; PG8_LDA(At, 1, 0); PG8_STAGE(PG8_SA(0, 1), a2 + hstepA, voffA);
;             PG8_WAIT_V(8); PG8_WAIT_L(0); PG8_BAR; PG8_MMA(0, 0, At, B0); PG8_MMA(0, 1, At, B1); PG8_BAR; PG8_SCHED;
;             PG8_LDA(At, 1, 1); PG8_STAGE(PG8_SB(1, 0), b3, voffB); PG8_STAGE(PG8_SB(1, 1), b3 + hstepB, voffB); PG8_STAGE(PG8_SA(1, 0), a3, voffA);
	s_waitcnt lgkmcnt(0)
	v_mfma_f32_16x16x32_bf16 v[64:67], v[142:145], v[200:203], 0
	v_mfma_f32_16x16x32_bf16 v[60:63], v[162:165], v[200:203], 0
	v_mfma_f32_16x16x32_bf16 v[48:51], v[142:145], v[208:211], 0
	v_mfma_f32_16x16x32_bf16 v[44:47], v[162:165], v[208:211], 0
	v_mfma_f32_16x16x32_bf16 v[32:35], v[142:145], v[216:219], 0
	v_mfma_f32_16x16x32_bf16 v[28:31], v[162:165], v[216:219], 0
	v_mfma_f32_16x16x32_bf16 v[16:19], v[142:145], v[224:227], 0
	v_mfma_f32_16x16x32_bf16 v[12:15], v[162:165], v[224:227], 0
	v_mfma_f32_16x16x32_bf16 v[64:67], v[154:157], v[204:207], v[64:67]
	v_mfma_f32_16x16x32_bf16 v[60:63], v[166:169], v[204:207], v[60:63]
	v_mfma_f32_16x16x32_bf16 v[48:51], v[154:157], v[212:215], v[48:51]
	v_mfma_f32_16x16x32_bf16 v[44:47], v[166:169], v[212:215], v[44:47]
	v_mfma_f32_16x16x32_bf16 v[32:35], v[154:157], v[220:223], v[32:35]
	v_mfma_f32_16x16x32_bf16 v[28:31], v[166:169], v[220:223], v[28:31]
	v_mfma_f32_16x16x32_bf16 v[16:19], v[154:157], v[228:231], v[16:19]
	v_mfma_f32_16x16x32_bf16 v[12:15], v[166:169], v[228:231], v[12:15]
	v_mfma_f32_16x16x32_bf16 v[56:59], v[170:173], v[200:203], 0
	v_mfma_f32_16x16x32_bf16 v[52:55], v[190:193], v[200:203], 0
	v_mfma_f32_16x16x32_bf16 v[40:43], v[170:173], v[208:211], 0
	v_mfma_f32_16x16x32_bf16 v[36:39], v[190:193], v[208:211], 0
	v_mfma_f32_16x16x32_bf16 v[24:27], v[170:173], v[216:219], 0
	v_mfma_f32_16x16x32_bf16 v[20:23], v[190:193], v[216:219], 0
	v_mfma_f32_16x16x32_bf16 v[8:11], v[170:173], v[224:227], 0
	v_mfma_f32_16x16x32_bf16 v[4:7], v[190:193], v[224:227], 0
	v_mfma_f32_16x16x32_bf16 v[56:59], v[174:177], v[204:207], v[56:59]
	v_mfma_f32_16x16x32_bf16 v[52:55], v[196:199], v[204:207], v[52:55]
	v_mfma_f32_16x16x32_bf16 v[40:43], v[174:177], v[212:215], v[40:43]
	v_mfma_f32_16x16x32_bf16 v[36:39], v[196:199], v[212:215], v[36:39]
	v_mfma_f32_16x16x32_bf16 v[24:27], v[174:177], v[220:223], v[24:27]
	v_mfma_f32_16x16x32_bf16 v[20:23], v[196:199], v[220:223], v[20:23]
	v_mfma_f32_16x16x32_bf16 v[8:11], v[174:177], v[228:231], v[8:11]
	v_mfma_f32_16x16x32_bf16 v[4:7], v[196:199], v[228:231], v[4:7]
	s_barrier
	s_add_i32 s0, 0, 0x18000
	v_add_u32_e32 v153, s0, v148
	s_add_i32 s26, 0, 0x1c000
	ds_read_b128 v[142:145], v153
	ds_read_b128 v[154:157], v153 offset:1024
	ds_read_b128 v[162:165], v153 offset:2048
	ds_read_b128 v[166:169], v153 offset:3072
	v_add_u32_e32 v153, s26, v148
	ds_read_b128 v[170:173], v153
	ds_read_b128 v[174:177], v153 offset:1024
	ds_read_b128 v[190:193], v153 offset:2048
	ds_read_b128 v[196:199], v153 offset:3072
	s_add_u32 s14, s14, 0x40000
	s_addc_u32 s15, s15, 0
	s_mov_b32 m0, s51
	v_lshl_add_u64 v[238:239], s[14:15], 0, v[132:133]
	ds_read_b128 v[200:203], v152 offset:32768
	ds_read_b128 v[204:207], v152 offset:33792
	ds_read_b128 v[208:211], v152 offset:34816
	ds_read_b128 v[212:215], v152 offset:35840
	ds_read_b128 v[216:219], v152 offset:36864
	ds_read_b128 v[220:223], v152 offset:37888
	ds_read_b128 v[224:227], v152 offset:38912
	ds_read_b128 v[228:231], v152 offset:39936
	global_load_lds_dwordx4 v[238:239], off
	v_lshl_add_u64 v[238:239], s[14:15], 0, v[134:135]
	s_mov_b32 m0, s52
	s_nop 0
	global_load_lds_dwordx4 v[238:239], off
	s_waitcnt vmcnt(8)
	s_waitcnt lgkmcnt(0)
	s_barrier
	s_waitcnt lgkmcnt(0)
	v_mfma_f32_16x16x32_bf16 v[128:131], v[142:145], v[200:203], v[128:131]
	v_mfma_f32_16x16x32_bf16 v[124:127], v[162:165], v[200:203], v[124:127]
	v_mfma_f32_16x16x32_bf16 v[112:115], v[142:145], v[208:211], v[112:115]
	v_mfma_f32_16x16x32_bf16 v[108:111], v[162:165], v[208:211], v[108:111]
	v_mfma_f32_16x16x32_bf16 v[96:99], v[142:145], v[216:219], v[96:99]
	v_mfma_f32_16x16x32_bf16 v[92:95], v[162:165], v[216:219], v[92:95]
	v_mfma_f32_16x16x32_bf16 v[80:83], v[142:145], v[224:227], v[80:83]
	v_mfma_f32_16x16x32_bf16 v[76:79], v[162:165], v[224:227], v[76:79]
	v_mfma_f32_16x16x32_bf16 v[128:131], v[154:157], v[204:207], v[128:131]
	v_mfma_f32_16x16x32_bf16 v[124:127], v[166:169], v[204:207], v[124:127]
	v_mfma_f32_16x16x32_bf16 v[112:115], v[154:157], v[212:215], v[112:115]
	v_mfma_f32_16x16x32_bf16 v[108:111], v[166:169], v[212:215], v[108:111]
	v_mfma_f32_16x16x32_bf16 v[96:99], v[154:157], v[220:223], v[96:99]
	v_mfma_f32_16x16x32_bf16 v[92:95], v[166:169], v[220:223], v[92:95]
	v_mfma_f32_16x16x32_bf16 v[80:83], v[154:157], v[228:231], v[80:83]
	v_mfma_f32_16x16x32_bf16 v[76:79], v[166:169], v[228:231], v[76:79]
	v_mfma_f32_16x16x32_bf16 v[120:123], v[170:173], v[200:203], v[120:123]
	v_mfma_f32_16x16x32_bf16 v[116:119], v[190:193], v[200:203], v[116:119]
	v_mfma_f32_16x16x32_bf16 v[104:107], v[170:173], v[208:211], v[104:107]
	v_mfma_f32_16x16x32_bf16 v[100:103], v[190:193], v[208:211], v[100:103]
	v_mfma_f32_16x16x32_bf16 v[88:91], v[170:173], v[216:219], v[88:91]
	v_mfma_f32_16x16x32_bf16 v[84:87], v[190:193], v[216:219], v[84:87]
	v_mfma_f32_16x16x32_bf16 v[72:75], v[170:173], v[224:227], v[72:75]
	v_mfma_f32_16x16x32_bf16 v[68:71], v[190:193], v[224:227], v[68:71]
	v_mfma_f32_16x16x32_bf16 v[120:123], v[174:177], v[204:207], v[120:123]
	v_mfma_f32_16x16x32_bf16 v[116:119], v[196:199], v[204:207], v[116:119]
	v_mfma_f32_16x16x32_bf16 v[104:107], v[174:177], v[212:215], v[104:107]
	v_mfma_f32_16x16x32_bf16 v[100:103], v[196:199], v[212:215], v[100:103]
	v_mfma_f32_16x16x32_bf16 v[88:91], v[174:177], v[220:223], v[88:91]
	v_mfma_f32_16x16x32_bf16 v[84:87], v[196:199], v[220:223], v[84:87]
	v_mfma_f32_16x16x32_bf16 v[72:75], v[174:177], v[228:231], v[72:75]
	v_mfma_f32_16x16x32_bf16 v[68:71], v[196:199], v[228:231], v[68:71]
	s_barrier
; #define PG8_STAGE(bufoff, gbase, voff) do { _Pragma("unroll") for (int _i = 0; _i < 2; ++_i) \
;         __builtin_amdgcn_global_load_lds((const unsigned*)((const char*)(gbase) + (voff)[_i]), (LAS unsigned*)(lds + (bufoff) + ldsw + _i * 8192), 16, 0, 0); } while (0)
; #define PG8_LDA(dst, b, h) do { _Pragma("unroll") for (int m = 0; m < 4; ++m) _Pragma("unroll") for (int k = 0; k < 2; ++k) dst[m][k] = *(const LAS bf16x8*)(lds + PG8_SA(b, h) + aoff + m * 2048 + k * 1024); } while (0)
; #define PG8_LDB(dst, b, h) do { _Pragma("unroll") for (int n = 0; n < 2; ++n) _Pragma("unroll") for (int k = 0; k < 2; ++k) dst[n][k] = *(const LAS bf16x8*)(lds + PG8_SB(b, h) + boff + n * 2048 + k * 1024); } while (0)
; #define PG8_MMA(ai, bj, At, Bt) do { __builtin_amdgcn_s_setprio(1); _Pragma("unroll") for (int m = 0; m < 4; ++m) _Pragma("unroll") for (int n = 0; n < 2; ++n) _Pragma("unroll") for (int k = 0; k < 2; ++k) \
;         acc[ai][bj][m][n] = __builtin_amdgcn_mfma_f32_16x16x32_bf16(Bt[n][k], At[m][k], acc[ai][bj][m][n], 0, 0, 0); __builtin_amdgcn_s_setprio(0); } while (0)
; #define PG8_WAIT_V(n) asm volatile("s_waitcnt vmcnt(" #n ")" ::: "memory")
; #define PG8_WAIT_L(n) asm volatile("s_waitcnt lgkmcnt(" #n ")" ::: "memory")
; #define PG8_BAR __builtin_amdgcn_s_barrier()
; #define PG8_SCHED __builtin_amdgcn_sched_barrier(0)
; template <class Epi, class Sched>
; __device__ __forceinline__ void gemm_phase(LAS unsigned char* lds, const Gemm g, const Sched& S, const Epi& E) {
;     ...
;             PG8_LDB(B0, 0, 0); PG8_LDB(B1, 0, 1); PG8_SCHED; PG8_LDA(At, 0, 0); PG8_STAGE(PG8_SA(1, 1), a1 + hstepA, voffA);
;             PG8_WAIT_V(8); PG8_WAIT_L(0); PG8_BAR; PG8_MMA(0, 0, At, B0); PG8_MMA(0, 1, At, B1); PG8_BAR; PG8_SCHED;
;     ...
;             PG8_LDA(At, 1, 1); PG8_STAGE(PG8_SB(1, 0), b3, voffB); PG8_STAGE(PG8_SB(1, 1), b3 + hstepB, voffB); PG8_STAGE(PG8_SA(1, 0), a3, voffA);
;             PG8_WAIT_V(8); PG8_WAIT_L(0); PG8_BAR; PG8_MMA(1, 0, At, B0); PG8_MMA(1, 1, At, B1); PG8_BAR; PG8_SCHED;
	s_add_i32 s0, s0, s20
	v_lshl_add_u64 v[158:159], v[158:159], 0, s[30:31]
	s_mov_b32 m0, s0
	ds_read_b128 v[200:203], v152 offset:49152
	ds_read_b128 v[204:207], v152 offset:50176
	ds_read_b128 v[208:211], v152 offset:51200
	ds_read_b128 v[212:215], v152 offset:52224
	ds_read_b128 v[216:219], v152 offset:53248
	ds_read_b128 v[220:223], v152 offset:54272
	ds_read_b128 v[224:227], v152 offset:55296
	ds_read_b128 v[228:231], v152 offset:56320
	global_load_lds_dwordx4 v[158:159], off
	s_add_i32 m0, s0, 0x2000
	s_add_u32 s6, s6, 0x40080
	v_lshl_add_u64 v[158:159], v[232:233], 0, s[30:31]
	s_addc_u32 s7, s7, 0
	s_add_i32 s0, s26, s20
	global_load_lds_dwordx4 v[158:159], off
	v_lshl_add_u64 v[158:159], s[6:7], 0, v[160:161]
	s_mov_b32 m0, s0
	s_nop 0
	global_load_lds_dwordx4 v[158:159], off
	v_lshl_add_u64 v[158:159], s[6:7], 0, v[136:137]
	s_add_i32 m0, s0, 0x2000
	s_nop 0
	global_load_lds_dwordx4 v[158:159], off
	v_lshl_add_u64 v[158:159], v[234:235], 0, s[30:31]
	s_mov_b32 m0, s24
	s_nop 0
	global_load_lds_dwordx4 v[158:159], off
	v_lshl_add_u64 v[158:159], v[236:237], 0, s[30:31]
	s_mov_b32 m0, s25
	s_nop 0
	global_load_lds_dwordx4 v[158:159], off
	s_waitcnt vmcnt(8)
	s_waitcnt lgkmcnt(0)
	s_barrier
	s_waitcnt lgkmcnt(0)
	v_mfma_f32_16x16x32_bf16 v[64:67], v[142:145], v[200:203], v[64:67]
	v_mfma_f32_16x16x32_bf16 v[60:63], v[162:165], v[200:203], v[60:63]
	v_mfma_f32_16x16x32_bf16 v[48:51], v[142:145], v[208:211], v[48:51]
	v_mfma_f32_16x16x32_bf16 v[44:47], v[162:165], v[208:211], v[44:47]
	v_mfma_f32_16x16x32_bf16 v[32:35], v[142:145], v[216:219], v[32:35]
	v_mfma_f32_16x16x32_bf16 v[28:31], v[162:165], v[216:219], v[28:31]
	v_mfma_f32_16x16x32_bf16 v[16:19], v[142:145], v[224:227], v[16:19]
	v_mfma_f32_16x16x32_bf16 v[12:15], v[162:165], v[224:227], v[12:15]
	v_mfma_f32_16x16x32_bf16 v[64:67], v[154:157], v[204:207], v[64:67]
	v_mfma_f32_16x16x32_bf16 v[60:63], v[166:169], v[204:207], v[60:63]
	v_mfma_f32_16x16x32_bf16 v[48:51], v[154:157], v[212:215], v[48:51]
	v_mfma_f32_16x16x32_bf16 v[44:47], v[166:169], v[212:215], v[44:47]
	v_mfma_f32_16x16x32_bf16 v[32:35], v[154:157], v[220:223], v[32:35]
	v_mfma_f32_16x16x32_bf16 v[28:31], v[166:169], v[220:223], v[28:31]
	v_mfma_f32_16x16x32_bf16 v[16:19], v[154:157], v[228:231], v[16:19]
	v_mfma_f32_16x16x32_bf16 v[12:15], v[166:169], v[228:231], v[12:15]
	v_mfma_f32_16x16x32_bf16 v[56:59], v[170:173], v[200:203], v[56:59]
	v_mfma_f32_16x16x32_bf16 v[52:55], v[190:193], v[200:203], v[52:55]
	v_mfma_f32_16x16x32_bf16 v[40:43], v[170:173], v[208:211], v[40:43]
	v_mfma_f32_16x16x32_bf16 v[36:39], v[190:193], v[208:211], v[36:39]
	v_mfma_f32_16x16x32_bf16 v[24:27], v[170:173], v[216:219], v[24:27]
	v_mfma_f32_16x16x32_bf16 v[20:23], v[190:193], v[216:219], v[20:23]
	v_mfma_f32_16x16x32_bf16 v[8:11], v[170:173], v[224:227], v[8:11]
	v_mfma_f32_16x16x32_bf16 v[4:7], v[190:193], v[224:227], v[4:7]
	v_mfma_f32_16x16x32_bf16 v[56:59], v[174:177], v[204:207], v[56:59]
	v_mfma_f32_16x16x32_bf16 v[52:55], v[196:199], v[204:207], v[52:55]
	v_mfma_f32_16x16x32_bf16 v[40:43], v[174:177], v[212:215], v[40:43]
	v_mfma_f32_16x16x32_bf16 v[36:39], v[196:199], v[212:215], v[36:39]
	v_mfma_f32_16x16x32_bf16 v[24:27], v[174:177], v[220:223], v[24:27]
	v_mfma_f32_16x16x32_bf16 v[20:23], v[196:199], v[220:223], v[20:23]
	v_mfma_f32_16x16x32_bf16 v[8:11], v[174:177], v[228:231], v[8:11]
	v_mfma_f32_16x16x32_bf16 v[4:7], v[196:199], v[228:231], v[4:7]
	s_barrier
	s_add_i32 s55, s55, 2
	s_add_u32 s44, s44, 0x100
	s_addc_u32 s45, s45, 0
	s_add_u32 s46, s46, 0x100
	s_addc_u32 s47, s47, 0
	s_cmp_gt_u32 s55, 13
.LBB0_718:
	s_add_u32 s0, s44, 0xfffc0080
	s_addc_u32 s6, s45, -1
	s_add_i32 s26, 0, 0x10000
	s_cmp_eq_u32 s55, 12
	s_cselect_b32 s15, s23, s6
	s_cselect_b32 s14, s53, s0
	v_add_u32_e32 v153, s26, v148
	s_cselect_b32 s7, s19, s47
	s_cselect_b32 s6, s54, s46
	s_add_i32 s0, 0, 0x14000
	ds_read_b128 v[142:145], v153
	ds_read_b128 v[154:157], v153 offset:1024
	ds_read_b128 v[162:165], v153 offset:2048
	ds_read_b128 v[166:169], v153 offset:3072
	v_add_u32_e32 v153, s0, v148
	ds_read_b128 v[170:173], v153
	ds_read_b128 v[174:177], v153 offset:1024
	ds_read_b128 v[190:193], v153 offset:2048
	ds_read_b128 v[196:199], v153 offset:3072
	v_lshl_add_u64 v[158:159], s[44:45], 0, v[138:139]
	s_add_i32 m0, s49, 0xc000
	ds_read_b128 v[200:203], v152
	ds_read_b128 v[204:207], v152 offset:1024
	ds_read_b128 v[208:211], v152 offset:2048
	ds_read_b128 v[212:215], v152 offset:3072
	ds_read_b128 v[216:219], v152 offset:4096
	ds_read_b128 v[220:223], v152 offset:5120
	ds_read_b128 v[224:227], v152 offset:6144
	ds_read_b128 v[228:231], v152 offset:7168
	global_load_lds_dwordx4 v[158:159], off
	v_lshl_add_u64 v[158:159], s[44:45], 0, v[140:141]
	s_add_i32 m0, s49, 0xe000
	s_nop 0
	global_load_lds_dwordx4 v[158:159], off
	s_waitcnt vmcnt(8)
	s_waitcnt lgkmcnt(0)
	s_barrier
; #define PG8_STAGE(bufoff, gbase, voff) do { _Pragma("unroll") for (int _i = 0; _i < 2; ++_i) \
;         __builtin_amdgcn_global_load_lds((const unsigned*)((const char*)(gbase) + (voff)[_i]), (LAS unsigned*)(lds + (bufoff) + ldsw + _i * 8192), 16, 0, 0); } while (0)
; #define PG8_LDA(dst, b, h) do { _Pragma("unroll") for (int m = 0; m < 4; ++m) _Pragma("unroll") for (int k = 0; k < 2; ++k) dst[m][k] = *(const LAS bf16x8*)(lds + PG8_SA(b, h) + aoff + m * 2048 + k * 1024); } while (0)
; #define PG8_LDB(dst, b, h) do { _Pragma("unroll") for (int n = 0; n < 2; ++n) _Pragma("unroll") for (int k = 0; k < 2; ++k) dst[n][k] = *(const LAS bf16x8*)(lds + PG8_SB(b, h) + boff + n * 2048 + k * 1024); } while (0)
; #define PG8_MMA(ai, bj, At, Bt) do { __builtin_amdgcn_s_setprio(1); _Pragma("unroll") for (int m = 0; m < 4; ++m) _Pragma("unroll") for (int n = 0; n < 2; ++n) _Pragma("unroll") for (int k = 0; k < 2; ++k) \
;         acc[ai][bj][m][n] = __builtin_amdgcn_mfma_f32_16x16x32_bf16(Bt[n][k], At[m][k], acc[ai][bj][m][n], 0, 0, 0); __builtin_amdgcn_s_setprio(0); } while (0)
; #define PG8_WAIT_V(n) asm volatile("s_waitcnt vmcnt(" #n ")" ::: "memory")
; #define PG8_WAIT_L(n) asm volatile("s_waitcnt lgkmcnt(" #n ")" ::: "memory")
; #define PG8_BAR __builtin_amdgcn_s_barrier()
; #define PG8_SCHED __builtin_amdgcn_sched_barrier(0)
; template <class Epi, class Sched>
; __device__ __forceinline__ void gemm_phase(LAS unsigned char* lds, const Gemm g, const Sched& S, const Epi& E) {
;     ...
;             PG8_WAIT_V(8); PG8_WAIT_L(0); PG8_BAR; PG8_MMA(0, 0, At, B0); PG8_MMA(0, 1, At, B1); PG8_BAR; PG8_SCHED;
;             PG8_LDA(At, 0, 1); PG8_STAGE(PG8_SB(0, 0), b2, voffB); PG8_STAGE(PG8_SB(0, 1), b2 + hstepB, voffB); PG8_STAGE(PG8_SA(0, 0), a2, voffA);
;             PG8_WAIT_V(8); PG8_WAIT_L(0); PG8_BAR; PG8_MMA(1, 0, At, B0); PG8_MMA(1, 1, At, B1); PG8_BAR; PG8_SCHED;
;             PG8_LDB(B0, 1, 0); PG8_LDB(B1, 1, 1); PG8_SCHED; PG8_LDA(At, 1, 0); PG8_STAGE(PG8_SA(0, 1), a2 + hstepA, voffA);
;             PG8_WAIT_V(8); PG8_WAIT_L(0); PG8_BAR; PG8_MMA(0, 0, At, B0); PG8_MMA(0, 1, At, B1); PG8_BAR; PG8_SCHED;
	s_waitcnt lgkmcnt(0)
	v_mfma_f32_16x16x32_bf16 v[128:131], v[142:145], v[200:203], v[128:131]
	v_mfma_f32_16x16x32_bf16 v[124:127], v[162:165], v[200:203], v[124:127]
	v_mfma_f32_16x16x32_bf16 v[112:115], v[142:145], v[208:211], v[112:115]
	v_mfma_f32_16x16x32_bf16 v[108:111], v[162:165], v[208:211], v[108:111]
	v_mfma_f32_16x16x32_bf16 v[96:99], v[142:145], v[216:219], v[96:99]
	v_mfma_f32_16x16x32_bf16 v[92:95], v[162:165], v[216:219], v[92:95]
	v_mfma_f32_16x16x32_bf16 v[80:83], v[142:145], v[224:227], v[80:83]
	v_mfma_f32_16x16x32_bf16 v[76:79], v[162:165], v[224:227], v[76:79]
	v_mfma_f32_16x16x32_bf16 v[128:131], v[154:157], v[204:207], v[128:131]
	v_mfma_f32_16x16x32_bf16 v[124:127], v[166:169], v[204:207], v[124:127]
	v_mfma_f32_16x16x32_bf16 v[112:115], v[154:157], v[212:215], v[112:115]
	v_mfma_f32_16x16x32_bf16 v[108:111], v[166:169], v[212:215], v[108:111]
	v_mfma_f32_16x16x32_bf16 v[96:99], v[154:157], v[220:223], v[96:99]
	v_mfma_f32_16x16x32_bf16 v[92:95], v[166:169], v[220:223], v[92:95]
	v_mfma_f32_16x16x32_bf16 v[80:83], v[154:157], v[228:231], v[80:83]
	v_mfma_f32_16x16x32_bf16 v[76:79], v[166:169], v[228:231], v[76:79]
	v_mfma_f32_16x16x32_bf16 v[120:123], v[170:173], v[200:203], v[120:123]
	v_mfma_f32_16x16x32_bf16 v[116:119], v[190:193], v[200:203], v[116:119]
	v_mfma_f32_16x16x32_bf16 v[104:107], v[170:173], v[208:211], v[104:107]
	v_mfma_f32_16x16x32_bf16 v[100:103], v[190:193], v[208:211], v[100:103]
	v_mfma_f32_16x16x32_bf16 v[88:91], v[170:173], v[216:219], v[88:91]
	v_mfma_f32_16x16x32_bf16 v[84:87], v[190:193], v[216:219], v[84:87]
	v_mfma_f32_16x16x32_bf16 v[72:75], v[170:173], v[224:227], v[72:75]
	v_mfma_f32_16x16x32_bf16 v[68:71], v[190:193], v[224:227], v[68:71]
	v_mfma_f32_16x16x32_bf16 v[120:123], v[174:177], v[204:207], v[120:123]
	v_mfma_f32_16x16x32_bf16 v[116:119], v[196:199], v[204:207], v[116:119]
	v_mfma_f32_16x16x32_bf16 v[104:107], v[174:177], v[212:215], v[104:107]
	v_mfma_f32_16x16x32_bf16 v[100:103], v[196:199], v[212:215], v[100:103]
	v_mfma_f32_16x16x32_bf16 v[88:91], v[174:177], v[220:223], v[88:91]
	v_mfma_f32_16x16x32_bf16 v[84:87], v[196:199], v[220:223], v[84:87]
	v_mfma_f32_16x16x32_bf16 v[72:75], v[174:177], v[228:231], v[72:75]
	v_mfma_f32_16x16x32_bf16 v[68:71], v[196:199], v[228:231], v[68:71]
	s_barrier
	s_add_i32 s26, s26, s20
	v_lshl_add_u64 v[158:159], s[6:7], 0, v[160:161]
	s_mov_b32 m0, s26
	ds_read_b128 v[200:203], v152 offset:16384
	ds_read_b128 v[204:207], v152 offset:17408
	ds_read_b128 v[208:211], v152 offset:18432
	ds_read_b128 v[212:215], v152 offset:19456
	ds_read_b128 v[216:219], v152 offset:20480
	ds_read_b128 v[220:223], v152 offset:21504
	ds_read_b128 v[224:227], v152 offset:22528
	ds_read_b128 v[228:231], v152 offset:23552
	global_load_lds_dwordx4 v[158:159], off
	s_add_i32 m0, s26, 0x2000
	s_add_u32 s56, s6, 0x40000
	v_lshl_add_u64 v[232:233], s[6:7], 0, v[136:137]
	s_addc_u32 s57, s7, 0
	s_add_i32 s0, s0, s20
	global_load_lds_dwordx4 v[232:233], off
	v_lshl_add_u64 v[234:235], s[56:57], 0, v[160:161]
	s_mov_b32 m0, s0
	v_lshl_add_u64 v[236:237], s[14:15], 0, v[134:135]
	global_load_lds_dwordx4 v[234:235], off
	v_lshl_add_u64 v[234:235], s[56:57], 0, v[136:137]
	s_add_i32 m0, s0, 0x2000
	s_nop 0
	global_load_lds_dwordx4 v[234:235], off
	v_lshl_add_u64 v[234:235], s[14:15], 0, v[132:133]
	s_mov_b32 m0, s49
	s_nop 0
	global_load_lds_dwordx4 v[234:235], off
	s_mov_b32 m0, s50
	s_nop 0
	global_load_lds_dwordx4 v[236:237], off
	s_waitcnt vmcnt(8)
	s_waitcnt lgkmcnt(0)
	s_barrier
	s_waitcnt lgkmcnt(0)
	v_mfma_f32_16x16x32_bf16 v[64:67], v[142:145], v[200:203], v[64:67]
	v_mfma_f32_16x16x32_bf16 v[60:63], v[162:165], v[200:203], v[60:63]
	v_mfma_f32_16x16x32_bf16 v[48:51], v[142:145], v[208:211], v[48:51]
	v_mfma_f32_16x16x32_bf16 v[44:47], v[162:165], v[208:211], v[44:47]
	v_mfma_f32_16x16x32_bf16 v[32:35], v[142:145], v[216:219], v[32:35]
	v_mfma_f32_16x16x32_bf16 v[28:31], v[162:165], v[216:219], v[28:31]
	v_mfma_f32_16x16x32_bf16 v[16:19], v[142:145], v[224:227], v[16:19]
	v_mfma_f32_16x16x32_bf16 v[12:15], v[162:165], v[224:227], v[12:15]
	v_mfma_f32_16x16x32_bf16 v[64:67], v[154:157], v[204:207], v[64:67]
	v_mfma_f32_16x16x32_bf16 v[60:63], v[166:169], v[204:207], v[60:63]
	v_mfma_f32_16x16x32_bf16 v[48:51], v[154:157], v[212:215], v[48:51]
	v_mfma_f32_16x16x32_bf16 v[44:47], v[166:169], v[212:215], v[44:47]
	v_mfma_f32_16x16x32_bf16 v[32:35], v[154:157], v[220:223], v[32:35]
	v_mfma_f32_16x16x32_bf16 v[28:31], v[166:169], v[220:223], v[28:31]
	v_mfma_f32_16x16x32_bf16 v[16:19], v[154:157], v[228:231], v[16:19]
	v_mfma_f32_16x16x32_bf16 v[12:15], v[166:169], v[228:231], v[12:15]
	v_mfma_f32_16x16x32_bf16 v[56:59], v[170:173], v[200:203], v[56:59]
	v_mfma_f32_16x16x32_bf16 v[52:55], v[190:193], v[200:203], v[52:55]
	v_mfma_f32_16x16x32_bf16 v[40:43], v[170:173], v[208:211], v[40:43]
	v_mfma_f32_16x16x32_bf16 v[36:39], v[190:193], v[208:211], v[36:39]
	v_mfma_f32_16x16x32_bf16 v[24:27], v[170:173], v[216:219], v[24:27]
	v_mfma_f32_16x16x32_bf16 v[20:23], v[190:193], v[216:219], v[20:23]
	v_mfma_f32_16x16x32_bf16 v[8:11], v[170:173], v[224:227], v[8:11]
	v_mfma_f32_16x16x32_bf16 v[4:7], v[190:193], v[224:227], v[4:7]
	v_mfma_f32_16x16x32_bf16 v[56:59], v[174:177], v[204:207], v[56:59]
	v_mfma_f32_16x16x32_bf16 v[52:55], v[196:199], v[204:207], v[52:55]
	v_mfma_f32_16x16x32_bf16 v[40:43], v[174:177], v[212:215], v[40:43]
	v_mfma_f32_16x16x32_bf16 v[36:39], v[196:199], v[212:215], v[36:39]
	v_mfma_f32_16x16x32_bf16 v[24:27], v[174:177], v[220:223], v[24:27]
	v_mfma_f32_16x16x32_bf16 v[20:23], v[196:199], v[220:223], v[20:23]
	v_mfma_f32_16x16x32_bf16 v[8:11], v[174:177], v[228:231], v[8:11]
	v_mfma_f32_16x16x32_bf16 v[4:7], v[196:199], v[228:231], v[4:7]
	s_barrier
; #define PG8_STAGE(bufoff, gbase, voff) do { _Pragma("unroll") for (int _i = 0; _i < 2; ++_i) \
;         __builtin_amdgcn_global_load_lds((const unsigned*)((const char*)(gbase) + (voff)[_i]), (LAS unsigned*)(lds + (bufoff) + ldsw + _i * 8192), 16, 0, 0); } while (0)
; #define PG8_LDA(dst, b, h) do { _Pragma("unroll") for (int m = 0; m < 4; ++m) _Pragma("unroll") for (int k = 0; k < 2; ++k) dst[m][k] = *(const LAS bf16x8*)(lds + PG8_SA(b, h) + aoff + m * 2048 + k * 1024); } while (0)
; #define PG8_LDB(dst, b, h) do { _Pragma("unroll") for (int n = 0; n < 2; ++n) _Pragma("unroll") for (int k = 0; k < 2; ++k) dst[n][k] = *(const LAS bf16x8*)(lds + PG8_SB(b, h) + boff + n * 2048 + k * 1024); } while (0)
; #define PG8_MMA(ai, bj, At, Bt) do { __builtin_amdgcn_s_setprio(1); _Pragma("unroll") for (int m = 0; m < 4; ++m) _Pragma("unroll") for (int n = 0; n < 2; ++n) _Pragma("unroll") for (int k = 0; k < 2; ++k) \
;         acc[ai][bj][m][n] = __builtin_amdgcn_mfma_f32_16x16x32_bf16(Bt[n][k], At[m][k], acc[ai][bj][m][n], 0, 0, 0); __builtin_amdgcn_s_setprio(0); } while (0)
; #define PG8_WAIT_V(n) asm volatile("s_waitcnt vmcnt(" #n ")" ::: "memory")
; #define PG8_WAIT_L(n) asm volatile("s_waitcnt lgkmcnt(" #n ")" ::: "memory")
; #define PG8_BAR __builtin_amdgcn_s_barrier()
; #define PG8_SCHED __builtin_amdgcn_sched_barrier(0)
; template <class Epi, class Sched>
; __device__ __forceinline__ void gemm_phase(LAS unsigned char* lds, const Gemm g, const Sched& S, const Epi& E) {
;     ...
;             PG8_LDB(B0, 1, 0); PG8_LDB(B1, 1, 1); PG8_SCHED; PG8_LDA(At, 1, 0); PG8_STAGE(PG8_SA(0, 1), a2 + hstepA, voffA);
;             PG8_WAIT_V(8); PG8_WAIT_L(0); PG8_BAR; PG8_MMA(0, 0, At, B0); PG8_MMA(0, 1, At, B1); PG8_BAR; PG8_SCHED;
	s_add_i32 s0, 0, 0x18000
	v_add_u32_e32 v153, s0, v148
	s_add_i32 s26, 0, 0x1c000
	ds_read_b128 v[142:145], v153
	ds_read_b128 v[154:157], v153 offset:1024
	ds_read_b128 v[162:165], v153 offset:2048
	ds_read_b128 v[166:169], v153 offset:3072
	v_add_u32_e32 v153, s26, v148
	ds_read_b128 v[170:173], v153
	ds_read_b128 v[174:177], v153 offset:1024
	ds_read_b128 v[190:193], v153 offset:2048
	ds_read_b128 v[196:199], v153 offset:3072
	s_add_u32 s14, s14, 0x40000
	s_addc_u32 s15, s15, 0
	s_mov_b32 m0, s51
	v_lshl_add_u64 v[238:239], s[14:15], 0, v[132:133]
	ds_read_b128 v[200:203], v152 offset:32768
	ds_read_b128 v[204:207], v152 offset:33792
	ds_read_b128 v[208:211], v152 offset:34816
	ds_read_b128 v[212:215], v152 offset:35840
	ds_read_b128 v[216:219], v152 offset:36864
	ds_read_b128 v[220:223], v152 offset:37888
	ds_read_b128 v[224:227], v152 offset:38912
	ds_read_b128 v[228:231], v152 offset:39936
	global_load_lds_dwordx4 v[238:239], off
	v_lshl_add_u64 v[238:239], s[14:15], 0, v[134:135]
	s_mov_b32 m0, s52
	s_nop 0
	global_load_lds_dwordx4 v[238:239], off
	s_waitcnt vmcnt(8)
	s_waitcnt lgkmcnt(0)
	s_barrier
	s_waitcnt lgkmcnt(0)
	v_mfma_f32_16x16x32_bf16 v[128:131], v[142:145], v[200:203], v[128:131]
	v_mfma_f32_16x16x32_bf16 v[124:127], v[162:165], v[200:203], v[124:127]
	v_mfma_f32_16x16x32_bf16 v[112:115], v[142:145], v[208:211], v[112:115]
	v_mfma_f32_16x16x32_bf16 v[108:111], v[162:165], v[208:211], v[108:111]
	v_mfma_f32_16x16x32_bf16 v[96:99], v[142:145], v[216:219], v[96:99]
	v_mfma_f32_16x16x32_bf16 v[92:95], v[162:165], v[216:219], v[92:95]
	v_mfma_f32_16x16x32_bf16 v[80:83], v[142:145], v[224:227], v[80:83]
	v_mfma_f32_16x16x32_bf16 v[76:79], v[162:165], v[224:227], v[76:79]
	v_mfma_f32_16x16x32_bf16 v[128:131], v[154:157], v[204:207], v[128:131]
	v_mfma_f32_16x16x32_bf16 v[124:127], v[166:169], v[204:207], v[124:127]
	v_mfma_f32_16x16x32_bf16 v[112:115], v[154:157], v[212:215], v[112:115]
	v_mfma_f32_16x16x32_bf16 v[108:111], v[166:169], v[212:215], v[108:111]
	v_mfma_f32_16x16x32_bf16 v[96:99], v[154:157], v[220:223], v[96:99]
	v_mfma_f32_16x16x32_bf16 v[92:95], v[166:169], v[220:223], v[92:95]
	v_mfma_f32_16x16x32_bf16 v[80:83], v[154:157], v[228:231], v[80:83]
	v_mfma_f32_16x16x32_bf16 v[76:79], v[166:169], v[228:231], v[76:79]
	v_mfma_f32_16x16x32_bf16 v[120:123], v[170:173], v[200:203], v[120:123]
	v_mfma_f32_16x16x32_bf16 v[116:119], v[190:193], v[200:203], v[116:119]
	v_mfma_f32_16x16x32_bf16 v[104:107], v[170:173], v[208:211], v[104:107]
	v_mfma_f32_16x16x32_bf16 v[100:103], v[190:193], v[208:211], v[100:103]
	v_mfma_f32_16x16x32_bf16 v[88:91], v[170:173], v[216:219], v[88:91]
	v_mfma_f32_16x16x32_bf16 v[84:87], v[190:193], v[216:219], v[84:87]
	v_mfma_f32_16x16x32_bf16 v[72:75], v[170:173], v[224:227], v[72:75]
	v_mfma_f32_16x16x32_bf16 v[68:71], v[190:193], v[224:227], v[68:71]
	v_mfma_f32_16x16x32_bf16 v[120:123], v[174:177], v[204:207], v[120:123]
	v_mfma_f32_16x16x32_bf16 v[116:119], v[196:199], v[204:207], v[116:119]
	v_mfma_f32_16x16x32_bf16 v[104:107], v[174:177], v[212:215], v[104:107]
	v_mfma_f32_16x16x32_bf16 v[100:103], v[196:199], v[212:215], v[100:103]
	v_mfma_f32_16x16x32_bf16 v[88:91], v[174:177], v[220:223], v[88:91]
	v_mfma_f32_16x16x32_bf16 v[84:87], v[196:199], v[220:223], v[84:87]
	v_mfma_f32_16x16x32_bf16 v[72:75], v[174:177], v[228:231], v[72:75]
	v_mfma_f32_16x16x32_bf16 v[68:71], v[196:199], v[228:231], v[68:71]
	s_barrier
; #define PG8_STAGE(bufoff, gbase, voff) do { _Pragma("unroll") for (int _i = 0; _i < 2; ++_i) \
;         __builtin_amdgcn_global_load_lds((const unsigned*)((const char*)(gbase) + (voff)[_i]), (LAS unsigned*)(lds + (bufoff) + ldsw + _i * 8192), 16, 0, 0); } while (0)
; #define PG8_LDA(dst, b, h) do { _Pragma("unroll") for (int m = 0; m < 4; ++m) _Pragma("unroll") for (int k = 0; k < 2; ++k) dst[m][k] = *(const LAS bf16x8*)(lds + PG8_SA(b, h) + aoff + m * 2048 + k * 1024); } while (0)
; #define PG8_MMA(ai, bj, At, Bt) do { __builtin_amdgcn_s_setprio(1); _Pragma("unroll") for (int m = 0; m < 4; ++m) _Pragma("unroll") for (int n = 0; n < 2; ++n) _Pragma("unroll") for (int k = 0; k < 2; ++k) \
;         acc[ai][bj][m][n] = __builtin_amdgcn_mfma_f32_16x16x32_bf16(Bt[n][k], At[m][k], acc[ai][bj][m][n], 0, 0, 0); __builtin_amdgcn_s_setprio(0); } while (0)
; #define PG8_WAIT_V(n) asm volatile("s_waitcnt vmcnt(" #n ")" ::: "memory")
; #define PG8_WAIT_L(n) asm volatile("s_waitcnt lgkmcnt(" #n ")" ::: "memory")
; #define PG8_BAR __builtin_amdgcn_s_barrier()
; #define PG8_SCHED __builtin_amdgcn_sched_barrier(0)
; template <class Epi, class Sched>
; __device__ __forceinline__ void gemm_phase(LAS unsigned char* lds, const Gemm g, const Sched& S, const Epi& E) {
;     ...
;             PG8_LDA(At, 1, 1); PG8_STAGE(PG8_SB(1, 0), b3, voffB); PG8_STAGE(PG8_SB(1, 1), b3 + hstepB, voffB); PG8_STAGE(PG8_SA(1, 0), a3, voffA);
;             PG8_WAIT_V(8); PG8_WAIT_L(0); PG8_BAR; PG8_MMA(1, 0, At, B0); PG8_MMA(1, 1, At, B1); PG8_BAR; PG8_SCHED;
;         }
;         if (wr == 0) PG8_BAR;
	s_add_i32 s0, s0, s20
	v_lshl_add_u64 v[158:159], v[158:159], 0, s[30:31]
	s_mov_b32 m0, s0
	ds_read_b128 v[200:203], v152 offset:49152
	ds_read_b128 v[204:207], v152 offset:50176
	ds_read_b128 v[208:211], v152 offset:51200
	ds_read_b128 v[212:215], v152 offset:52224
	ds_read_b128 v[216:219], v152 offset:53248
	ds_read_b128 v[220:223], v152 offset:54272
	ds_read_b128 v[224:227], v152 offset:55296
	ds_read_b128 v[228:231], v152 offset:56320
	global_load_lds_dwordx4 v[158:159], off
	s_add_i32 m0, s0, 0x2000
	s_add_u32 s6, s6, 0x40080
	v_lshl_add_u64 v[158:159], v[232:233], 0, s[30:31]
	s_addc_u32 s7, s7, 0
	s_add_i32 s0, s26, s20
	global_load_lds_dwordx4 v[158:159], off
	v_lshl_add_u64 v[158:159], s[6:7], 0, v[160:161]
	s_mov_b32 m0, s0
	s_nop 0
	global_load_lds_dwordx4 v[158:159], off
	v_lshl_add_u64 v[158:159], s[6:7], 0, v[136:137]
	s_add_i32 m0, s0, 0x2000
	s_nop 0
	global_load_lds_dwordx4 v[158:159], off
	v_lshl_add_u64 v[158:159], v[234:235], 0, s[30:31]
	s_mov_b32 m0, s24
	s_nop 0
	global_load_lds_dwordx4 v[158:159], off
	v_lshl_add_u64 v[158:159], v[236:237], 0, s[30:31]
	s_mov_b32 m0, s25
	s_nop 0
	global_load_lds_dwordx4 v[158:159], off
	s_waitcnt vmcnt(8)
	s_waitcnt lgkmcnt(0)
	s_barrier
	s_waitcnt lgkmcnt(0)
	v_mfma_f32_16x16x32_bf16 v[64:67], v[142:145], v[200:203], v[64:67]
	v_mfma_f32_16x16x32_bf16 v[60:63], v[162:165], v[200:203], v[60:63]
	v_mfma_f32_16x16x32_bf16 v[48:51], v[142:145], v[208:211], v[48:51]
	v_mfma_f32_16x16x32_bf16 v[44:47], v[162:165], v[208:211], v[44:47]
	v_mfma_f32_16x16x32_bf16 v[32:35], v[142:145], v[216:219], v[32:35]
	v_mfma_f32_16x16x32_bf16 v[28:31], v[162:165], v[216:219], v[28:31]
	v_mfma_f32_16x16x32_bf16 v[16:19], v[142:145], v[224:227], v[16:19]
	v_mfma_f32_16x16x32_bf16 v[12:15], v[162:165], v[224:227], v[12:15]
	v_mfma_f32_16x16x32_bf16 v[64:67], v[154:157], v[204:207], v[64:67]
	v_mfma_f32_16x16x32_bf16 v[60:63], v[166:169], v[204:207], v[60:63]
	v_mfma_f32_16x16x32_bf16 v[48:51], v[154:157], v[212:215], v[48:51]
	v_mfma_f32_16x16x32_bf16 v[44:47], v[166:169], v[212:215], v[44:47]
	v_mfma_f32_16x16x32_bf16 v[32:35], v[154:157], v[220:223], v[32:35]
	v_mfma_f32_16x16x32_bf16 v[28:31], v[166:169], v[220:223], v[28:31]
	v_mfma_f32_16x16x32_bf16 v[16:19], v[154:157], v[228:231], v[16:19]
	v_mfma_f32_16x16x32_bf16 v[12:15], v[166:169], v[228:231], v[12:15]
	v_mfma_f32_16x16x32_bf16 v[56:59], v[170:173], v[200:203], v[56:59]
	v_mfma_f32_16x16x32_bf16 v[52:55], v[190:193], v[200:203], v[52:55]
	v_mfma_f32_16x16x32_bf16 v[40:43], v[170:173], v[208:211], v[40:43]
	v_mfma_f32_16x16x32_bf16 v[36:39], v[190:193], v[208:211], v[36:39]
	v_mfma_f32_16x16x32_bf16 v[24:27], v[170:173], v[216:219], v[24:27]
	v_mfma_f32_16x16x32_bf16 v[20:23], v[190:193], v[216:219], v[20:23]
	v_mfma_f32_16x16x32_bf16 v[8:11], v[170:173], v[224:227], v[8:11]
	v_mfma_f32_16x16x32_bf16 v[4:7], v[190:193], v[224:227], v[4:7]
	v_mfma_f32_16x16x32_bf16 v[56:59], v[174:177], v[204:207], v[56:59]
	v_mfma_f32_16x16x32_bf16 v[52:55], v[196:199], v[204:207], v[52:55]
	v_mfma_f32_16x16x32_bf16 v[40:43], v[174:177], v[212:215], v[40:43]
	v_mfma_f32_16x16x32_bf16 v[36:39], v[196:199], v[212:215], v[36:39]
	v_mfma_f32_16x16x32_bf16 v[24:27], v[174:177], v[220:223], v[24:27]
	v_mfma_f32_16x16x32_bf16 v[20:23], v[196:199], v[220:223], v[20:23]
	v_mfma_f32_16x16x32_bf16 v[8:11], v[174:177], v[228:231], v[8:11]
	v_mfma_f32_16x16x32_bf16 v[4:7], v[196:199], v[228:231], v[4:7]
	s_barrier
	s_add_i32 s55, s55, 2
	s_add_u32 s44, s44, 0x100
	s_addc_u32 s45, s45, 0
	s_add_u32 s46, s46, 0x100
	s_addc_u32 s47, s47, 0
	s_cmp_gt_u32 s55, 13
	s_cbranch_scc0 .LBB0_718
	s_setprio 0
	s_and_b64 vcc, exec, s[16:17]
	s_cbranch_vccz .LBB0_721
	s_barrier
